# P12 ffn conv+GLU item rewritten by hand: lane walks its own 64-row chunk (conv history as partial sums in registers, no cross-lane shuffles), rows streamed by LDS-DMA ring 7 rows ahead
# speedup vs baseline: 1.0122x; 1.0074x over previous
; __device__ __forceinline__ void ffn_conv_item(int tid_in, int b, int strip, bf16_t* h1, const bf16_t* h2, const float* cw, const float* cb, bool st = true) {
;     int tid_ = tid_in; asm volatile("" : "+v"(tid_)); const int tid = tid_, lane = tid & 63, wid = __builtin_amdgcn_readfirstlane(tid >> 6), rl = lane >> 3, cg = lane & 7;
;     const int ch = 64 * strip + 8 * cg;
;     float wg[3][8], wv[3][8], bg[8], bv[8];
; #pragma unroll
;     for (int j = 0; j < 3; ++j) { const f32x4 a = *(const f32x4*)(cw + j * 11264 + ch), c = *(const f32x4*)(cw + j * 11264 + ch + 4), a2 = *(const f32x4*)(cw + j * 11264 + 5632 + ch), c2 = *(const f32x4*)(cw + j * 11264 + 5632 + ch + 4);
; #pragma unroll
;         for (int e = 0; e < 4; ++e) { wg[j][e] = a[e]; wg[j][4 + e] = c[e]; wv[j][e] = a2[e]; wv[j][4 + e] = c2[e]; } }
;     { const f32x4 a = *(const f32x4*)(cb + ch), c = *(const f32x4*)(cb + ch + 4), a2 = *(const f32x4*)(cb + 5632 + ch), c2 = *(const f32x4*)(cb + 5632 + ch + 4);
; #pragma unroll
;       for (int e = 0; e < 4; ++e) { bg[e] = a[e]; bg[4 + e] = c[e]; bv[e] = a2[e]; bv[4 + e] = c2[e]; } }
;     const size_t off0 = ((size_t)b * SEQL + 512 * wid) * 5632 + ch;
;     u32x4 pg = {0u, 0u, 0u, 0u}, pv = {0u, 0u, 0u, 0u};
;     if (wid > 0) { pg = *(const u32x4*)(h1 + off0 + (ptrdiff_t)(rl - 8) * 5632); pv = *(const u32x4*)(h2 + off0 + (ptrdiff_t)(rl - 8) * 5632); }
;     asm volatile("s_waitcnt vmcnt(0)" ::: "memory");
;     __syncthreads();
;     u32x4 cg4[4], cv4[4];
; #pragma unroll
;     for (int j = 0; j < 4; ++j) { cg4[j] = __builtin_nontemporal_load((const u32x4*)(h1 + off0 + (size_t)(8 * j + rl) * 5632)); cv4[j] = __builtin_nontemporal_load((const u32x4*)(h2 + off0 + (size_t)(8 * j + rl) * 5632)); }
.LBB0_18:
	s_waitcnt lgkmcnt(0)
	s_mul_hi_i32 s9, s8, 0x2e8ba2e9
	s_lshr_b32 s18, s9, 31
	s_ashr_i32 s9, s9, 4
	s_add_i32 s18, s9, s18
	s_mul_i32 s9, s18, 0x58
	s_sub_i32 s9, s8, s9
	v_and_b32_e32 v0, 63, v146
	v_lshrrev_b32_e32 v159, 3, v0
	v_and_b32_e32 v160, 7, v0
	v_mul_u32_u24_e32 v159, 0xb0000, v159
	v_lshl_add_u32 v159, v160, 4, v159
	s_lshl_b32 s19, s9, 8
	v_lshl_add_u32 v156, v160, 5, s19
	v_lshlrev_b32_e32 v160, 4, v0
	s_lshl_b32 s12, s58, 14
	v_add_u32_e32 v160, s12, v160
	v_add_u32_e32 v148, 0x5800, v156
	v_add_u32_e32 v149, 0xb000, v156
	v_add_u32_e32 v150, 0x10800, v156
	v_add_u32_e32 v151, 0x16000, v156
	v_add_u32_e32 v152, 0x1b800, v156
	global_load_dwordx4 v[2:5], v156, s[44:45]
	global_load_dwordx4 v[6:9], v156, s[44:45] offset:16
	global_load_dwordx4 v[10:13], v148, s[44:45]
	global_load_dwordx4 v[14:17], v148, s[44:45] offset:16
	global_load_dwordx4 v[18:21], v149, s[44:45]
	global_load_dwordx4 v[22:25], v149, s[44:45] offset:16
	global_load_dwordx4 v[26:29], v150, s[44:45]
	global_load_dwordx4 v[30:33], v150, s[44:45] offset:16
	global_load_dwordx4 v[34:37], v151, s[44:45]
	global_load_dwordx4 v[38:41], v151, s[44:45] offset:16
	global_load_dwordx4 v[42:45], v152, s[44:45]
	global_load_dwordx4 v[46:49], v152, s[44:45] offset:16
	global_load_dwordx4 v[50:53], v156, s[46:47]
	global_load_dwordx4 v[54:57], v156, s[46:47] offset:16
	global_load_dwordx4 v[58:61], v148, s[46:47]
	global_load_dwordx4 v[62:65], v148, s[46:47] offset:16
	s_lshl_b32 s19, s18, 12
	s_lshl_b32 s20, s58, 9
	s_add_i32 s19, s19, s20
	s_mul_i32 s19, s19, 0x2c00
	s_lshl_b32 s20, s9, 7
	s_add_i32 s19, s19, s20
	s_add_u32 s40, s66, 0x4a00000
	s_addc_u32 s41, s67, 0
	s_add_u32 s40, s40, s19
	s_addc_u32 s41, s41, 0
	s_sub_u32 s20, s40, 0x2c00
	s_subb_u32 s21, s41, 0
	s_sub_u32 s22, s40, 0x5800
	s_subb_u32 s23, s41, 0
	s_add_u32 s24, s20, 0xb000000
	s_addc_u32 s25, s21, 0
	s_add_u32 s28, s22, 0xb000000
	s_addc_u32 s29, s23, 0
	v_mov_b32_e32 v98, 0
	v_mov_b32_e32 v99, 0
	v_mov_b32_e32 v100, 0
	v_mov_b32_e32 v101, 0
	v_mov_b32_e32 v102, 0
	v_mov_b32_e32 v103, 0
	v_mov_b32_e32 v104, 0
	v_mov_b32_e32 v105, 0
	v_mov_b32_e32 v106, 0
	v_mov_b32_e32 v107, 0
	v_mov_b32_e32 v108, 0
	v_mov_b32_e32 v109, 0
	v_mov_b32_e32 v110, 0
	v_mov_b32_e32 v111, 0
	v_mov_b32_e32 v112, 0
	v_mov_b32_e32 v113, 0
	s_mov_b64 s[18:19], -1
	s_cmp_lg_u32 s58, 0
	s_cbranch_scc1 .Lcv_hm
	s_mov_b32 s18, 0xffffff00
.Lcv_hm:
	s_mov_b64 exec, s[18:19]
	global_load_dwordx4 v[98:101], v159, s[20:21]
	global_load_dwordx4 v[102:105], v159, s[24:25]
	global_load_dwordx4 v[106:109], v159, s[22:23]
	global_load_dwordx4 v[110:113], v159, s[28:29]
	s_mov_b64 exec, -1
	s_mov_b32 s42, s40
	s_mov_b32 s43, s41
	s_add_i32 m0, s12, 0x0
	s_add_u32 s26, s42, 0xb000000
	s_addc_u32 s27, s43, 0
	global_load_lds_dwordx4 v159, s[42:43] nt
	s_add_i32 m0, s12, 0x400
	s_add_u32 s42, s42, 0x2c00
	s_addc_u32 s43, s43, 0
	global_load_lds_dwordx4 v159, s[26:27] nt
	s_add_i32 m0, s12, 0x800
	s_add_u32 s26, s42, 0xb000000
	s_addc_u32 s27, s43, 0
	global_load_lds_dwordx4 v159, s[42:43] nt
	s_add_i32 m0, s12, 0xc00
	s_add_u32 s42, s42, 0x2c00
	s_addc_u32 s43, s43, 0
	global_load_lds_dwordx4 v159, s[26:27] nt
	s_add_i32 m0, s12, 0x1000
	s_add_u32 s26, s42, 0xb000000
	s_addc_u32 s27, s43, 0
	global_load_lds_dwordx4 v159, s[42:43] nt
	s_add_i32 m0, s12, 0x1400
	s_add_u32 s42, s42, 0x2c00
	s_addc_u32 s43, s43, 0
	global_load_lds_dwordx4 v159, s[26:27] nt
	s_add_i32 m0, s12, 0x1800
	s_add_u32 s26, s42, 0xb000000
	s_addc_u32 s27, s43, 0
	global_load_lds_dwordx4 v159, s[42:43] nt
	s_add_i32 m0, s12, 0x1c00
	s_add_u32 s42, s42, 0x2c00
	s_addc_u32 s43, s43, 0
	global_load_lds_dwordx4 v159, s[26:27] nt
	s_add_i32 m0, s12, 0x2000
	s_add_u32 s26, s42, 0xb000000
	s_addc_u32 s27, s43, 0
	global_load_lds_dwordx4 v159, s[42:43] nt
	s_add_i32 m0, s12, 0x2400
	s_add_u32 s42, s42, 0x2c00
	s_addc_u32 s43, s43, 0
	global_load_lds_dwordx4 v159, s[26:27] nt
	s_add_i32 m0, s12, 0x2800
	s_add_u32 s26, s42, 0xb000000
	s_addc_u32 s27, s43, 0
	global_load_lds_dwordx4 v159, s[42:43] nt
	s_add_i32 m0, s12, 0x2c00
	s_add_u32 s42, s42, 0x2c00
	s_addc_u32 s43, s43, 0
	global_load_lds_dwordx4 v159, s[26:27] nt
	s_add_i32 m0, s12, 0x3000
	s_add_u32 s26, s42, 0xb000000
	s_addc_u32 s27, s43, 0
	global_load_lds_dwordx4 v159, s[42:43] nt
	s_add_i32 m0, s12, 0x3400
	s_add_u32 s42, s42, 0x2c00
	s_addc_u32 s43, s43, 0
	global_load_lds_dwordx4 v159, s[26:27] nt
	s_movk_i32 s9, 7
	s_mov_b32 s34, 0xbfb8aa3b
	s_mov_b32 s35, 0xbfb8aa3b
	s_mov_b32 s13, 0
	s_waitcnt vmcnt(14)
	v_lshlrev_b32_e32 v114, 16, v98
	v_and_b32_e32 v115, 0xffff0000, v98
	v_lshlrev_b32_e32 v116, 16, v99
	v_and_b32_e32 v117, 0xffff0000, v99
	v_lshlrev_b32_e32 v118, 16, v100
	v_and_b32_e32 v119, 0xffff0000, v100
	v_lshlrev_b32_e32 v120, 16, v101
	v_and_b32_e32 v121, 0xffff0000, v101
	v_lshlrev_b32_e32 v122, 16, v102
	v_and_b32_e32 v123, 0xffff0000, v102
	v_lshlrev_b32_e32 v124, 16, v103
	v_and_b32_e32 v125, 0xffff0000, v103
	v_lshlrev_b32_e32 v126, 16, v104
	v_and_b32_e32 v127, 0xffff0000, v104
	v_lshlrev_b32_e32 v128, 16, v105
	v_and_b32_e32 v129, 0xffff0000, v105
	v_lshlrev_b32_e32 v130, 16, v106
	v_and_b32_e32 v131, 0xffff0000, v106
	v_lshlrev_b32_e32 v132, 16, v107
	v_and_b32_e32 v133, 0xffff0000, v107
	v_lshlrev_b32_e32 v134, 16, v108
	v_and_b32_e32 v135, 0xffff0000, v108
	v_lshlrev_b32_e32 v136, 16, v109
	v_and_b32_e32 v137, 0xffff0000, v109
	v_lshlrev_b32_e32 v138, 16, v110
	v_and_b32_e32 v139, 0xffff0000, v110
	v_lshlrev_b32_e32 v140, 16, v111
	v_and_b32_e32 v141, 0xffff0000, v111
	v_lshlrev_b32_e32 v142, 16, v112
	v_and_b32_e32 v143, 0xffff0000, v112
	v_lshlrev_b32_e32 v144, 16, v113
	v_and_b32_e32 v145, 0xffff0000, v113
	v_pk_fma_f32 v[66:67], v[2:3], v[130:131], v[50:51]
	v_pk_fma_f32 v[68:69], v[4:5], v[132:133], v[52:53]
	v_pk_fma_f32 v[70:71], v[6:7], v[134:135], v[54:55]
	v_pk_fma_f32 v[72:73], v[8:9], v[136:137], v[56:57]
	v_pk_fma_f32 v[74:75], v[10:11], v[138:139], v[58:59]
	v_pk_fma_f32 v[76:77], v[12:13], v[140:141], v[60:61]
	v_pk_fma_f32 v[78:79], v[14:15], v[142:143], v[62:63]
	v_pk_fma_f32 v[80:81], v[16:17], v[144:145], v[64:65]
	v_pk_fma_f32 v[66:67], v[18:19], v[114:115], v[66:67]
	v_pk_fma_f32 v[68:69], v[20:21], v[116:117], v[68:69]
	v_pk_fma_f32 v[70:71], v[22:23], v[118:119], v[70:71]
	v_pk_fma_f32 v[72:73], v[24:25], v[120:121], v[72:73]
	v_pk_fma_f32 v[74:75], v[26:27], v[122:123], v[74:75]
	v_pk_fma_f32 v[76:77], v[28:29], v[124:125], v[76:77]
	v_pk_fma_f32 v[78:79], v[30:31], v[126:127], v[78:79]
	v_pk_fma_f32 v[80:81], v[32:33], v[128:129], v[80:81]
	v_pk_fma_f32 v[82:83], v[2:3], v[114:115], v[50:51]
	v_pk_fma_f32 v[84:85], v[4:5], v[116:117], v[52:53]
	v_pk_fma_f32 v[86:87], v[6:7], v[118:119], v[54:55]
	v_pk_fma_f32 v[88:89], v[8:9], v[120:121], v[56:57]
	v_pk_fma_f32 v[90:91], v[10:11], v[122:123], v[58:59]
	v_pk_fma_f32 v[92:93], v[12:13], v[124:125], v[60:61]
	v_pk_fma_f32 v[94:95], v[14:15], v[126:127], v[62:63]
	v_pk_fma_f32 v[96:97], v[16:17], v[128:129], v[64:65]
	s_barrier
; __device__ __forceinline__ float sigm(float x) { return 1.f / (1.f + __expf(-x)); }
; __device__ __forceinline__ u32x4 pack8(const float (&f)[8]) { u32x4 w; w.x = pk2(f[0], f[1]); w.y = pk2(f[2], f[3]); w.z = pk2(f[4], f[5]); w.w = pk2(f[6], f[7]); return w; }
; __device__ __forceinline__ void ffn_conv_item(int tid_in, int b, int strip, bf16_t* h1, const bf16_t* h2, const float* cw, const float* cb, bool st = true) {
;     ...
;     for (int blk = 0; blk < 16; ++blk) {
;         u32x4 ng4[4], nv4[4];
;         if (blk + 1 < 16) {
; #pragma unroll
;             for (int j = 0; j < 4; ++j) { const size_t o_ = off0 + (size_t)(32 * (blk + 1) + 8 * j + rl) * 5632; ng4[j] = __builtin_nontemporal_load((const u32x4*)(h1 + o_)); nv4[j] = __builtin_nontemporal_load((const u32x4*)(h2 + o_)); }
;         }
; #pragma unroll
;         for (int j = 0; j < 4; ++j) {
;             const size_t off = off0 + (size_t)(32 * blk + 8 * j + rl) * 5632;
;             const u32x4 cgv = cg4[j], cvv = cv4[j];
;             float xg[8], xv[8], yg[8], yv[8]; unpack8(cgv, xg); unpack8(cvv, xv);
; #pragma unroll
;             for (int e = 0; e < 8; ++e) { yg[e] = bg[e] + wg[2][e] * xg[e]; yv[e] = bv[e] + wv[2][e] * xv[e]; }
; #pragma unroll
;             for (int d = 1; d <= 2; ++d) {
;                 const bool own = (rl + d <= 7); const int src = (lane + 64 - 8 * d) & 63;
;                 const u32x4 sg = own ? cgv : pg, sv = own ? cvv : pv;
;                 u32x4 g, v; g.x = __shfl(sg.x, src); g.y = __shfl(sg.y, src); g.z = __shfl(sg.z, src); g.w = __shfl(sg.w, src);
;                 v.x = __shfl(sv.x, src); v.y = __shfl(sv.y, src); v.z = __shfl(sv.z, src); v.w = __shfl(sv.w, src);
;                 float dg[8], dv[8]; unpack8(g, dg); unpack8(v, dv);
; #pragma unroll
;                 for (int e = 0; e < 8; ++e) { yg[e] += wg[2 - d][e] * dg[e]; yv[e] += wv[2 - d][e] * dv[e]; }
;             }
; #pragma unroll
;             for (int e = 0; e < 8; ++e) yg[e] = yg[e] * sigm(yg[e]) * yv[e];
;             { const u32x4 o_ = pack8(yg); if (st) *(u32x4*)(h1 + off) = o_; else asm volatile("" :: "v"(o_)); }
;             pg = cgv; pv = cvv;
;         }
	s_waitcnt vmcnt(0)
	ds_read_b128 v[98:101], v160
	ds_read_b128 v[102:105], v160 offset:1024
.Lcv_loop:
	s_waitcnt vmcnt(16)
	ds_read_b128 v[106:109], v160 offset:2048
	ds_read_b128 v[110:113], v160 offset:3072
	s_cmp_gt_u32 s9, 63
	s_cbranch_scc1 .Lcv_dum0
	s_add_i32 m0, s12, 0x3800
	s_add_u32 s26, s42, 0xb000000
	s_addc_u32 s27, s43, 0
	global_load_lds_dwordx4 v159, s[42:43] nt
	s_add_i32 m0, s12, 0x3c00
	s_add_u32 s42, s42, 0x2c00
	s_addc_u32 s43, s43, 0
	global_load_lds_dwordx4 v159, s[26:27] nt
	s_branch .Lcv_join0
.Lcv_dum0:
	global_load_dword v147, v1, s[40:41]
	global_load_dword v147, v1, s[40:41]
.Lcv_join0:
	s_add_i32 s9, s9, 1
	s_waitcnt lgkmcnt(2)
	v_lshlrev_b32_e32 v114, 16, v98
	v_and_b32_e32 v115, 0xffff0000, v98
	v_lshlrev_b32_e32 v116, 16, v99
	v_and_b32_e32 v117, 0xffff0000, v99
	v_lshlrev_b32_e32 v118, 16, v100
	v_and_b32_e32 v119, 0xffff0000, v100
	v_lshlrev_b32_e32 v120, 16, v101
	v_and_b32_e32 v121, 0xffff0000, v101
	v_lshlrev_b32_e32 v122, 16, v102
	v_and_b32_e32 v123, 0xffff0000, v102
	v_lshlrev_b32_e32 v124, 16, v103
	v_and_b32_e32 v125, 0xffff0000, v103
	v_lshlrev_b32_e32 v126, 16, v104
	v_and_b32_e32 v127, 0xffff0000, v104
	v_lshlrev_b32_e32 v128, 16, v105
	v_and_b32_e32 v129, 0xffff0000, v105
	v_pk_fma_f32 v[130:131], v[34:35], v[114:115], v[66:67]
	v_pk_fma_f32 v[132:133], v[36:37], v[116:117], v[68:69]
	v_pk_fma_f32 v[134:135], v[38:39], v[118:119], v[70:71]
	v_pk_fma_f32 v[136:137], v[40:41], v[120:121], v[72:73]
	v_pk_fma_f32 v[138:139], v[42:43], v[122:123], v[74:75]
	v_pk_fma_f32 v[140:141], v[44:45], v[124:125], v[76:77]
	v_pk_fma_f32 v[142:143], v[46:47], v[126:127], v[78:79]
	v_pk_fma_f32 v[144:145], v[48:49], v[128:129], v[80:81]
	v_pk_fma_f32 v[66:67], v[18:19], v[114:115], v[82:83]
	v_pk_fma_f32 v[68:69], v[20:21], v[116:117], v[84:85]
	v_pk_fma_f32 v[70:71], v[22:23], v[118:119], v[86:87]
	v_pk_fma_f32 v[72:73], v[24:25], v[120:121], v[88:89]
	v_pk_fma_f32 v[74:75], v[26:27], v[122:123], v[90:91]
	v_pk_fma_f32 v[76:77], v[28:29], v[124:125], v[92:93]
	v_pk_fma_f32 v[78:79], v[30:31], v[126:127], v[94:95]
	v_pk_fma_f32 v[80:81], v[32:33], v[128:129], v[96:97]
	v_pk_fma_f32 v[82:83], v[2:3], v[114:115], v[50:51]
	v_pk_fma_f32 v[84:85], v[4:5], v[116:117], v[52:53]
	v_pk_fma_f32 v[86:87], v[6:7], v[118:119], v[54:55]
	v_pk_fma_f32 v[88:89], v[8:9], v[120:121], v[56:57]
	v_pk_fma_f32 v[90:91], v[10:11], v[122:123], v[58:59]
	v_pk_fma_f32 v[92:93], v[12:13], v[124:125], v[60:61]
	v_pk_fma_f32 v[94:95], v[14:15], v[126:127], v[62:63]
	v_pk_fma_f32 v[96:97], v[16:17], v[128:129], v[64:65]
	v_pk_mul_f32 v[148:149], v[130:131], s[34:35]
	v_pk_mul_f32 v[150:151], v[132:133], s[34:35]
	v_pk_mul_f32 v[152:153], v[134:135], s[34:35]
	v_pk_mul_f32 v[154:155], v[136:137], s[34:35]
	v_exp_f32_e32 v148, v148
	v_exp_f32_e32 v149, v149
	v_exp_f32_e32 v150, v150
	v_exp_f32_e32 v151, v151
	v_exp_f32_e32 v152, v152
	v_exp_f32_e32 v153, v153
	v_exp_f32_e32 v154, v154
	v_exp_f32_e32 v155, v155
	v_pk_add_f32 v[148:149], v[148:149], 1.0 op_sel_hi:[1,0]
	v_pk_add_f32 v[150:151], v[150:151], 1.0 op_sel_hi:[1,0]
	v_pk_add_f32 v[152:153], v[152:153], 1.0 op_sel_hi:[1,0]
	v_pk_add_f32 v[154:155], v[154:155], 1.0 op_sel_hi:[1,0]
	v_rcp_f32_e32 v148, v148
	v_rcp_f32_e32 v149, v149
	v_rcp_f32_e32 v150, v150
	v_rcp_f32_e32 v151, v151
	v_rcp_f32_e32 v152, v152
	v_rcp_f32_e32 v153, v153
	v_rcp_f32_e32 v154, v154
	v_rcp_f32_e32 v155, v155
	v_pk_mul_f32 v[130:131], v[130:131], v[148:149]
	v_pk_mul_f32 v[132:133], v[132:133], v[150:151]
	v_pk_mul_f32 v[134:135], v[134:135], v[152:153]
	v_pk_mul_f32 v[136:137], v[136:137], v[154:155]
	v_pk_mul_f32 v[130:131], v[130:131], v[138:139]
	v_pk_mul_f32 v[132:133], v[132:133], v[140:141]
	v_pk_mul_f32 v[134:135], v[134:135], v[142:143]
	v_pk_mul_f32 v[136:137], v[136:137], v[144:145]
	v_cvt_pk_bf16_f32 v148, v130, v131
	v_cvt_pk_bf16_f32 v149, v132, v133
	v_cvt_pk_bf16_f32 v150, v134, v135
	v_cvt_pk_bf16_f32 v151, v136, v137
	global_store_dwordx4 v159, v[148:151], s[40:41]
	s_add_u32 s40, s40, 0x2c00
	s_addc_u32 s41, s41, 0
	s_waitcnt vmcnt(16)
	ds_read_b128 v[98:101], v160 offset:4096
	ds_read_b128 v[102:105], v160 offset:5120
	s_cmp_gt_u32 s9, 63
	s_cbranch_scc1 .Lcv_dum1
	s_add_i32 m0, s12, 0x0
	s_add_u32 s26, s42, 0xb000000
	s_addc_u32 s27, s43, 0
	global_load_lds_dwordx4 v159, s[42:43] nt
	s_add_i32 m0, s12, 0x400
	s_add_u32 s42, s42, 0x2c00
	s_addc_u32 s43, s43, 0
	global_load_lds_dwordx4 v159, s[26:27] nt
	s_branch .Lcv_join1

; __device__ __forceinline__ float sigm(float x) { return 1.f / (1.f + __expf(-x)); }
; __device__ __forceinline__ u32x4 pack8(const float (&f)[8]) { u32x4 w; w.x = pk2(f[0], f[1]); w.y = pk2(f[2], f[3]); w.z = pk2(f[4], f[5]); w.w = pk2(f[6], f[7]); return w; }
; __device__ __forceinline__ void ffn_conv_item(int tid_in, int b, int strip, bf16_t* h1, const bf16_t* h2, const float* cw, const float* cb, bool st = true) {
;     ...
;         for (int j = 0; j < 4; ++j) {
;             const size_t off = off0 + (size_t)(32 * blk + 8 * j + rl) * 5632;
;             const u32x4 cgv = cg4[j], cvv = cv4[j];
;             float xg[8], xv[8], yg[8], yv[8]; unpack8(cgv, xg); unpack8(cvv, xv);
; #pragma unroll
;             for (int e = 0; e < 8; ++e) { yg[e] = bg[e] + wg[2][e] * xg[e]; yv[e] = bv[e] + wv[2][e] * xv[e]; }
; #pragma unroll
;             for (int d = 1; d <= 2; ++d) {
;                 const bool own = (rl + d <= 7); const int src = (lane + 64 - 8 * d) & 63;
;                 const u32x4 sg = own ? cgv : pg, sv = own ? cvv : pv;
;                 u32x4 g, v; g.x = __shfl(sg.x, src); g.y = __shfl(sg.y, src); g.z = __shfl(sg.z, src); g.w = __shfl(sg.w, src);
;                 v.x = __shfl(sv.x, src); v.y = __shfl(sv.y, src); v.z = __shfl(sv.z, src); v.w = __shfl(sv.w, src);
;                 float dg[8], dv[8]; unpack8(g, dg); unpack8(v, dv);
; #pragma unroll
;                 for (int e = 0; e < 8; ++e) { yg[e] += wg[2 - d][e] * dg[e]; yv[e] += wv[2 - d][e] * dv[e]; }
;             }
; #pragma unroll
;             for (int e = 0; e < 8; ++e) yg[e] = yg[e] * sigm(yg[e]) * yv[e];
;             { const u32x4 o_ = pack8(yg); if (st) *(u32x4*)(h1 + off) = o_; else asm volatile("" :: "v"(o_)); }
;             pg = cgv; pv = cvv;
;         }
.Lcv_join1:
	s_add_i32 s9, s9, 1
	s_waitcnt lgkmcnt(2)
	v_lshlrev_b32_e32 v114, 16, v106
	v_and_b32_e32 v115, 0xffff0000, v106
	v_lshlrev_b32_e32 v116, 16, v107
	v_and_b32_e32 v117, 0xffff0000, v107
	v_lshlrev_b32_e32 v118, 16, v108
	v_and_b32_e32 v119, 0xffff0000, v108
	v_lshlrev_b32_e32 v120, 16, v109
	v_and_b32_e32 v121, 0xffff0000, v109
	v_lshlrev_b32_e32 v122, 16, v110
	v_and_b32_e32 v123, 0xffff0000, v110
	v_lshlrev_b32_e32 v124, 16, v111
	v_and_b32_e32 v125, 0xffff0000, v111
	v_lshlrev_b32_e32 v126, 16, v112
	v_and_b32_e32 v127, 0xffff0000, v112
	v_lshlrev_b32_e32 v128, 16, v113
	v_and_b32_e32 v129, 0xffff0000, v113
	v_pk_fma_f32 v[130:131], v[34:35], v[114:115], v[66:67]
	v_pk_fma_f32 v[132:133], v[36:37], v[116:117], v[68:69]
	v_pk_fma_f32 v[134:135], v[38:39], v[118:119], v[70:71]
	v_pk_fma_f32 v[136:137], v[40:41], v[120:121], v[72:73]
	v_pk_fma_f32 v[138:139], v[42:43], v[122:123], v[74:75]
	v_pk_fma_f32 v[140:141], v[44:45], v[124:125], v[76:77]
	v_pk_fma_f32 v[142:143], v[46:47], v[126:127], v[78:79]
	v_pk_fma_f32 v[144:145], v[48:49], v[128:129], v[80:81]
	v_pk_fma_f32 v[66:67], v[18:19], v[114:115], v[82:83]
	v_pk_fma_f32 v[68:69], v[20:21], v[116:117], v[84:85]
	v_pk_fma_f32 v[70:71], v[22:23], v[118:119], v[86:87]
	v_pk_fma_f32 v[72:73], v[24:25], v[120:121], v[88:89]
	v_pk_fma_f32 v[74:75], v[26:27], v[122:123], v[90:91]
	v_pk_fma_f32 v[76:77], v[28:29], v[124:125], v[92:93]
	v_pk_fma_f32 v[78:79], v[30:31], v[126:127], v[94:95]
	v_pk_fma_f32 v[80:81], v[32:33], v[128:129], v[96:97]
	v_pk_fma_f32 v[82:83], v[2:3], v[114:115], v[50:51]
	v_pk_fma_f32 v[84:85], v[4:5], v[116:117], v[52:53]
	v_pk_fma_f32 v[86:87], v[6:7], v[118:119], v[54:55]
	v_pk_fma_f32 v[88:89], v[8:9], v[120:121], v[56:57]
	v_pk_fma_f32 v[90:91], v[10:11], v[122:123], v[58:59]
	v_pk_fma_f32 v[92:93], v[12:13], v[124:125], v[60:61]
	v_pk_fma_f32 v[94:95], v[14:15], v[126:127], v[62:63]
	v_pk_fma_f32 v[96:97], v[16:17], v[128:129], v[64:65]
	v_pk_mul_f32 v[148:149], v[130:131], s[34:35]
	v_pk_mul_f32 v[150:151], v[132:133], s[34:35]
	v_pk_mul_f32 v[152:153], v[134:135], s[34:35]
	v_pk_mul_f32 v[154:155], v[136:137], s[34:35]
	v_exp_f32_e32 v148, v148
	v_exp_f32_e32 v149, v149
	v_exp_f32_e32 v150, v150
	v_exp_f32_e32 v151, v151
	v_exp_f32_e32 v152, v152
	v_exp_f32_e32 v153, v153
	v_exp_f32_e32 v154, v154
	v_exp_f32_e32 v155, v155
	v_pk_add_f32 v[148:149], v[148:149], 1.0 op_sel_hi:[1,0]
	v_pk_add_f32 v[150:151], v[150:151], 1.0 op_sel_hi:[1,0]
	v_pk_add_f32 v[152:153], v[152:153], 1.0 op_sel_hi:[1,0]
	v_pk_add_f32 v[154:155], v[154:155], 1.0 op_sel_hi:[1,0]
	v_rcp_f32_e32 v148, v148
	v_rcp_f32_e32 v149, v149
	v_rcp_f32_e32 v150, v150
	v_rcp_f32_e32 v151, v151
	v_rcp_f32_e32 v152, v152
	v_rcp_f32_e32 v153, v153
	v_rcp_f32_e32 v154, v154
	v_rcp_f32_e32 v155, v155
	v_pk_mul_f32 v[130:131], v[130:131], v[148:149]
	v_pk_mul_f32 v[132:133], v[132:133], v[150:151]
	v_pk_mul_f32 v[134:135], v[134:135], v[152:153]
	v_pk_mul_f32 v[136:137], v[136:137], v[154:155]
	v_pk_mul_f32 v[130:131], v[130:131], v[138:139]
	v_pk_mul_f32 v[132:133], v[132:133], v[140:141]
	v_pk_mul_f32 v[134:135], v[134:135], v[142:143]
	v_pk_mul_f32 v[136:137], v[136:137], v[144:145]
	v_cvt_pk_bf16_f32 v148, v130, v131
	v_cvt_pk_bf16_f32 v149, v132, v133
	v_cvt_pk_bf16_f32 v150, v134, v135
	v_cvt_pk_bf16_f32 v151, v136, v137
	global_store_dwordx4 v159, v[148:151], s[40:41]
	s_add_u32 s40, s40, 0x2c00
	s_addc_u32 s41, s41, 0
	s_waitcnt vmcnt(16)
	ds_read_b128 v[106:109], v160 offset:6144
	ds_read_b128 v[110:113], v160 offset:7168
	s_cmp_gt_u32 s9, 63
	s_cbranch_scc1 .Lcv_dum2
	s_add_i32 m0, s12, 0x800
	s_add_u32 s26, s42, 0xb000000
	s_addc_u32 s27, s43, 0
	global_load_lds_dwordx4 v159, s[42:43] nt
	s_add_i32 m0, s12, 0xc00
	s_add_u32 s42, s42, 0x2c00
	s_addc_u32 s43, s43, 0
	global_load_lds_dwordx4 v159, s[26:27] nt
	s_branch .Lcv_join2

; __device__ __forceinline__ float sigm(float x) { return 1.f / (1.f + __expf(-x)); }
; __device__ __forceinline__ u32x4 pack8(const float (&f)[8]) { u32x4 w; w.x = pk2(f[0], f[1]); w.y = pk2(f[2], f[3]); w.z = pk2(f[4], f[5]); w.w = pk2(f[6], f[7]); return w; }
; __device__ __forceinline__ void ffn_conv_item(int tid_in, int b, int strip, bf16_t* h1, const bf16_t* h2, const float* cw, const float* cb, bool st = true) {
;     ...
;         for (int j = 0; j < 4; ++j) {
;             const size_t off = off0 + (size_t)(32 * blk + 8 * j + rl) * 5632;
;             const u32x4 cgv = cg4[j], cvv = cv4[j];
;             float xg[8], xv[8], yg[8], yv[8]; unpack8(cgv, xg); unpack8(cvv, xv);
; #pragma unroll
;             for (int e = 0; e < 8; ++e) { yg[e] = bg[e] + wg[2][e] * xg[e]; yv[e] = bv[e] + wv[2][e] * xv[e]; }
; #pragma unroll
;             for (int d = 1; d <= 2; ++d) {
;                 const bool own = (rl + d <= 7); const int src = (lane + 64 - 8 * d) & 63;
;                 const u32x4 sg = own ? cgv : pg, sv = own ? cvv : pv;
;                 u32x4 g, v; g.x = __shfl(sg.x, src); g.y = __shfl(sg.y, src); g.z = __shfl(sg.z, src); g.w = __shfl(sg.w, src);
;                 v.x = __shfl(sv.x, src); v.y = __shfl(sv.y, src); v.z = __shfl(sv.z, src); v.w = __shfl(sv.w, src);
;                 float dg[8], dv[8]; unpack8(g, dg); unpack8(v, dv);
; #pragma unroll
;                 for (int e = 0; e < 8; ++e) { yg[e] += wg[2 - d][e] * dg[e]; yv[e] += wv[2 - d][e] * dv[e]; }
;             }
; #pragma unroll
;             for (int e = 0; e < 8; ++e) yg[e] = yg[e] * sigm(yg[e]) * yv[e];
;             { const u32x4 o_ = pack8(yg); if (st) *(u32x4*)(h1 + off) = o_; else asm volatile("" :: "v"(o_)); }
;             pg = cgv; pv = cvv;
;         }
.Lcv_join2:
	s_add_i32 s9, s9, 1
	s_waitcnt lgkmcnt(2)
	v_lshlrev_b32_e32 v114, 16, v98
	v_and_b32_e32 v115, 0xffff0000, v98
	v_lshlrev_b32_e32 v116, 16, v99
	v_and_b32_e32 v117, 0xffff0000, v99
	v_lshlrev_b32_e32 v118, 16, v100
	v_and_b32_e32 v119, 0xffff0000, v100
	v_lshlrev_b32_e32 v120, 16, v101
	v_and_b32_e32 v121, 0xffff0000, v101
	v_lshlrev_b32_e32 v122, 16, v102
	v_and_b32_e32 v123, 0xffff0000, v102
	v_lshlrev_b32_e32 v124, 16, v103
	v_and_b32_e32 v125, 0xffff0000, v103
	v_lshlrev_b32_e32 v126, 16, v104
	v_and_b32_e32 v127, 0xffff0000, v104
	v_lshlrev_b32_e32 v128, 16, v105
	v_and_b32_e32 v129, 0xffff0000, v105
	v_pk_fma_f32 v[130:131], v[34:35], v[114:115], v[66:67]
	v_pk_fma_f32 v[132:133], v[36:37], v[116:117], v[68:69]
	v_pk_fma_f32 v[134:135], v[38:39], v[118:119], v[70:71]
	v_pk_fma_f32 v[136:137], v[40:41], v[120:121], v[72:73]
	v_pk_fma_f32 v[138:139], v[42:43], v[122:123], v[74:75]
	v_pk_fma_f32 v[140:141], v[44:45], v[124:125], v[76:77]
	v_pk_fma_f32 v[142:143], v[46:47], v[126:127], v[78:79]
	v_pk_fma_f32 v[144:145], v[48:49], v[128:129], v[80:81]
	v_pk_fma_f32 v[66:67], v[18:19], v[114:115], v[82:83]
	v_pk_fma_f32 v[68:69], v[20:21], v[116:117], v[84:85]
	v_pk_fma_f32 v[70:71], v[22:23], v[118:119], v[86:87]
	v_pk_fma_f32 v[72:73], v[24:25], v[120:121], v[88:89]
	v_pk_fma_f32 v[74:75], v[26:27], v[122:123], v[90:91]
	v_pk_fma_f32 v[76:77], v[28:29], v[124:125], v[92:93]
	v_pk_fma_f32 v[78:79], v[30:31], v[126:127], v[94:95]
	v_pk_fma_f32 v[80:81], v[32:33], v[128:129], v[96:97]
	v_pk_fma_f32 v[82:83], v[2:3], v[114:115], v[50:51]
	v_pk_fma_f32 v[84:85], v[4:5], v[116:117], v[52:53]
	v_pk_fma_f32 v[86:87], v[6:7], v[118:119], v[54:55]
	v_pk_fma_f32 v[88:89], v[8:9], v[120:121], v[56:57]
	v_pk_fma_f32 v[90:91], v[10:11], v[122:123], v[58:59]
	v_pk_fma_f32 v[92:93], v[12:13], v[124:125], v[60:61]
	v_pk_fma_f32 v[94:95], v[14:15], v[126:127], v[62:63]
	v_pk_fma_f32 v[96:97], v[16:17], v[128:129], v[64:65]
	v_pk_mul_f32 v[148:149], v[130:131], s[34:35]
	v_pk_mul_f32 v[150:151], v[132:133], s[34:35]
	v_pk_mul_f32 v[152:153], v[134:135], s[34:35]
	v_pk_mul_f32 v[154:155], v[136:137], s[34:35]
	v_exp_f32_e32 v148, v148
	v_exp_f32_e32 v149, v149
	v_exp_f32_e32 v150, v150
	v_exp_f32_e32 v151, v151
	v_exp_f32_e32 v152, v152
	v_exp_f32_e32 v153, v153
	v_exp_f32_e32 v154, v154
	v_exp_f32_e32 v155, v155
	v_pk_add_f32 v[148:149], v[148:149], 1.0 op_sel_hi:[1,0]
	v_pk_add_f32 v[150:151], v[150:151], 1.0 op_sel_hi:[1,0]
	v_pk_add_f32 v[152:153], v[152:153], 1.0 op_sel_hi:[1,0]
	v_pk_add_f32 v[154:155], v[154:155], 1.0 op_sel_hi:[1,0]
	v_rcp_f32_e32 v148, v148
	v_rcp_f32_e32 v149, v149
	v_rcp_f32_e32 v150, v150
	v_rcp_f32_e32 v151, v151
	v_rcp_f32_e32 v152, v152
	v_rcp_f32_e32 v153, v153
	v_rcp_f32_e32 v154, v154
	v_rcp_f32_e32 v155, v155
	v_pk_mul_f32 v[130:131], v[130:131], v[148:149]
	v_pk_mul_f32 v[132:133], v[132:133], v[150:151]
	v_pk_mul_f32 v[134:135], v[134:135], v[152:153]
	v_pk_mul_f32 v[136:137], v[136:137], v[154:155]
	v_pk_mul_f32 v[130:131], v[130:131], v[138:139]
	v_pk_mul_f32 v[132:133], v[132:133], v[140:141]
	v_pk_mul_f32 v[134:135], v[134:135], v[142:143]
	v_pk_mul_f32 v[136:137], v[136:137], v[144:145]
	v_cvt_pk_bf16_f32 v148, v130, v131
	v_cvt_pk_bf16_f32 v149, v132, v133
	v_cvt_pk_bf16_f32 v150, v134, v135
	v_cvt_pk_bf16_f32 v151, v136, v137
	global_store_dwordx4 v159, v[148:151], s[40:41]
	s_add_u32 s40, s40, 0x2c00
	s_addc_u32 s41, s41, 0
	s_waitcnt vmcnt(16)
	ds_read_b128 v[98:101], v160 offset:8192
	ds_read_b128 v[102:105], v160 offset:9216
	s_cmp_gt_u32 s9, 63
	s_cbranch_scc1 .Lcv_dum3
	s_add_i32 m0, s12, 0x1000
	s_add_u32 s26, s42, 0xb000000
	s_addc_u32 s27, s43, 0
	global_load_lds_dwordx4 v159, s[42:43] nt
	s_add_i32 m0, s12, 0x1400
	s_add_u32 s42, s42, 0x2c00
	s_addc_u32 s43, s43, 0
	global_load_lds_dwordx4 v159, s[26:27] nt
	s_branch .Lcv_join3

; __device__ __forceinline__ float sigm(float x) { return 1.f / (1.f + __expf(-x)); }
; __device__ __forceinline__ u32x4 pack8(const float (&f)[8]) { u32x4 w; w.x = pk2(f[0], f[1]); w.y = pk2(f[2], f[3]); w.z = pk2(f[4], f[5]); w.w = pk2(f[6], f[7]); return w; }
; __device__ __forceinline__ void ffn_conv_item(int tid_in, int b, int strip, bf16_t* h1, const bf16_t* h2, const float* cw, const float* cb, bool st = true) {
;     ...
;         for (int j = 0; j < 4; ++j) {
;             const size_t off = off0 + (size_t)(32 * blk + 8 * j + rl) * 5632;
;             const u32x4 cgv = cg4[j], cvv = cv4[j];
;             float xg[8], xv[8], yg[8], yv[8]; unpack8(cgv, xg); unpack8(cvv, xv);
; #pragma unroll
;             for (int e = 0; e < 8; ++e) { yg[e] = bg[e] + wg[2][e] * xg[e]; yv[e] = bv[e] + wv[2][e] * xv[e]; }
; #pragma unroll
;             for (int d = 1; d <= 2; ++d) {
;                 const bool own = (rl + d <= 7); const int src = (lane + 64 - 8 * d) & 63;
;                 const u32x4 sg = own ? cgv : pg, sv = own ? cvv : pv;
;                 u32x4 g, v; g.x = __shfl(sg.x, src); g.y = __shfl(sg.y, src); g.z = __shfl(sg.z, src); g.w = __shfl(sg.w, src);
;                 v.x = __shfl(sv.x, src); v.y = __shfl(sv.y, src); v.z = __shfl(sv.z, src); v.w = __shfl(sv.w, src);
;                 float dg[8], dv[8]; unpack8(g, dg); unpack8(v, dv);
; #pragma unroll
;                 for (int e = 0; e < 8; ++e) { yg[e] += wg[2 - d][e] * dg[e]; yv[e] += wv[2 - d][e] * dv[e]; }
;             }
; #pragma unroll
;             for (int e = 0; e < 8; ++e) yg[e] = yg[e] * sigm(yg[e]) * yv[e];
;             { const u32x4 o_ = pack8(yg); if (st) *(u32x4*)(h1 + off) = o_; else asm volatile("" :: "v"(o_)); }
;             pg = cgv; pv = cvv;
;         }
.Lcv_join3:
	s_add_i32 s9, s9, 1
	s_waitcnt lgkmcnt(2)
	v_lshlrev_b32_e32 v114, 16, v106
	v_and_b32_e32 v115, 0xffff0000, v106
	v_lshlrev_b32_e32 v116, 16, v107
	v_and_b32_e32 v117, 0xffff0000, v107
	v_lshlrev_b32_e32 v118, 16, v108
	v_and_b32_e32 v119, 0xffff0000, v108
	v_lshlrev_b32_e32 v120, 16, v109
	v_and_b32_e32 v121, 0xffff0000, v109
	v_lshlrev_b32_e32 v122, 16, v110
	v_and_b32_e32 v123, 0xffff0000, v110
	v_lshlrev_b32_e32 v124, 16, v111
	v_and_b32_e32 v125, 0xffff0000, v111
	v_lshlrev_b32_e32 v126, 16, v112
	v_and_b32_e32 v127, 0xffff0000, v112
	v_lshlrev_b32_e32 v128, 16, v113
	v_and_b32_e32 v129, 0xffff0000, v113
	v_pk_fma_f32 v[130:131], v[34:35], v[114:115], v[66:67]
	v_pk_fma_f32 v[132:133], v[36:37], v[116:117], v[68:69]
	v_pk_fma_f32 v[134:135], v[38:39], v[118:119], v[70:71]
	v_pk_fma_f32 v[136:137], v[40:41], v[120:121], v[72:73]
	v_pk_fma_f32 v[138:139], v[42:43], v[122:123], v[74:75]
	v_pk_fma_f32 v[140:141], v[44:45], v[124:125], v[76:77]
	v_pk_fma_f32 v[142:143], v[46:47], v[126:127], v[78:79]
	v_pk_fma_f32 v[144:145], v[48:49], v[128:129], v[80:81]
	v_pk_fma_f32 v[66:67], v[18:19], v[114:115], v[82:83]
	v_pk_fma_f32 v[68:69], v[20:21], v[116:117], v[84:85]
	v_pk_fma_f32 v[70:71], v[22:23], v[118:119], v[86:87]
	v_pk_fma_f32 v[72:73], v[24:25], v[120:121], v[88:89]
	v_pk_fma_f32 v[74:75], v[26:27], v[122:123], v[90:91]
	v_pk_fma_f32 v[76:77], v[28:29], v[124:125], v[92:93]
	v_pk_fma_f32 v[78:79], v[30:31], v[126:127], v[94:95]
	v_pk_fma_f32 v[80:81], v[32:33], v[128:129], v[96:97]
	v_pk_fma_f32 v[82:83], v[2:3], v[114:115], v[50:51]
	v_pk_fma_f32 v[84:85], v[4:5], v[116:117], v[52:53]
	v_pk_fma_f32 v[86:87], v[6:7], v[118:119], v[54:55]
	v_pk_fma_f32 v[88:89], v[8:9], v[120:121], v[56:57]
	v_pk_fma_f32 v[90:91], v[10:11], v[122:123], v[58:59]
	v_pk_fma_f32 v[92:93], v[12:13], v[124:125], v[60:61]
	v_pk_fma_f32 v[94:95], v[14:15], v[126:127], v[62:63]
	v_pk_fma_f32 v[96:97], v[16:17], v[128:129], v[64:65]
	v_pk_mul_f32 v[148:149], v[130:131], s[34:35]
	v_pk_mul_f32 v[150:151], v[132:133], s[34:35]
	v_pk_mul_f32 v[152:153], v[134:135], s[34:35]
	v_pk_mul_f32 v[154:155], v[136:137], s[34:35]
	v_exp_f32_e32 v148, v148
	v_exp_f32_e32 v149, v149
	v_exp_f32_e32 v150, v150
	v_exp_f32_e32 v151, v151
	v_exp_f32_e32 v152, v152
	v_exp_f32_e32 v153, v153
	v_exp_f32_e32 v154, v154
	v_exp_f32_e32 v155, v155
	v_pk_add_f32 v[148:149], v[148:149], 1.0 op_sel_hi:[1,0]
	v_pk_add_f32 v[150:151], v[150:151], 1.0 op_sel_hi:[1,0]
	v_pk_add_f32 v[152:153], v[152:153], 1.0 op_sel_hi:[1,0]
	v_pk_add_f32 v[154:155], v[154:155], 1.0 op_sel_hi:[1,0]
	v_rcp_f32_e32 v148, v148
	v_rcp_f32_e32 v149, v149
	v_rcp_f32_e32 v150, v150
	v_rcp_f32_e32 v151, v151
	v_rcp_f32_e32 v152, v152
	v_rcp_f32_e32 v153, v153
	v_rcp_f32_e32 v154, v154
	v_rcp_f32_e32 v155, v155
	v_pk_mul_f32 v[130:131], v[130:131], v[148:149]
	v_pk_mul_f32 v[132:133], v[132:133], v[150:151]
	v_pk_mul_f32 v[134:135], v[134:135], v[152:153]
	v_pk_mul_f32 v[136:137], v[136:137], v[154:155]
	v_pk_mul_f32 v[130:131], v[130:131], v[138:139]
	v_pk_mul_f32 v[132:133], v[132:133], v[140:141]
	v_pk_mul_f32 v[134:135], v[134:135], v[142:143]
	v_pk_mul_f32 v[136:137], v[136:137], v[144:145]
	v_cvt_pk_bf16_f32 v148, v130, v131
	v_cvt_pk_bf16_f32 v149, v132, v133
	v_cvt_pk_bf16_f32 v150, v134, v135
	v_cvt_pk_bf16_f32 v151, v136, v137
	global_store_dwordx4 v159, v[148:151], s[40:41]
	s_add_u32 s40, s40, 0x2c00
	s_addc_u32 s41, s41, 0
	s_waitcnt vmcnt(16)
	ds_read_b128 v[106:109], v160 offset:10240
	ds_read_b128 v[110:113], v160 offset:11264
	s_cmp_gt_u32 s9, 63
	s_cbranch_scc1 .Lcv_dum4
	s_add_i32 m0, s12, 0x1800
	s_add_u32 s26, s42, 0xb000000
	s_addc_u32 s27, s43, 0
	global_load_lds_dwordx4 v159, s[42:43] nt
	s_add_i32 m0, s12, 0x1c00
	s_add_u32 s42, s42, 0x2c00
	s_addc_u32 s43, s43, 0
	global_load_lds_dwordx4 v159, s[26:27] nt
	s_branch .Lcv_join4

; __device__ __forceinline__ void ffn_conv_item(int tid_in, int b, int strip, bf16_t* h1, const bf16_t* h2, const float* cw, const float* cb, bool st = true) {
;     ...
;             for (int d = 1; d <= 2; ++d) {
;                 const bool own = (rl + d <= 7); const int src = (lane + 64 - 8 * d) & 63;
;                 const u32x4 sg = own ? cgv : pg, sv = own ? cvv : pv;
;                 u32x4 g, v; g.x = __shfl(sg.x, src); g.y = __shfl(sg.y, src); g.z = __shfl(sg.z, src); g.w = __shfl(sg.w, src);
;                 v.x = __shfl(sv.x, src); v.y = __shfl(sv.y, src); v.z = __shfl(sv.z, src); v.w = __shfl(sv.w, src);
;                 float dg[8], dv[8]; unpack8(g, dg); unpack8(v, dv);
; #pragma unroll
;                 for (int e = 0; e < 8; ++e) { yg[e] += wg[2 - d][e] * dg[e]; yv[e] += wv[2 - d][e] * dv[e]; }
;             }
.Lcv_join4:
	s_add_i32 s9, s9, 1
	s_waitcnt lgkmcnt(2)
	v_lshlrev_b32_e32 v114, 16, v98
	v_and_b32_e32 v115, 0xffff0000, v98
	v_lshlrev_b32_e32 v116, 16, v99
	v_and_b32_e32 v117, 0xffff0000, v99
	v_lshlrev_b32_e32 v118, 16, v100
	v_and_b32_e32 v119, 0xffff0000, v100
	v_lshlrev_b32_e32 v120, 16, v101
	v_and_b32_e32 v121, 0xffff0000, v101
	v_lshlrev_b32_e32 v122, 16, v102
	v_and_b32_e32 v123, 0xffff0000, v102
	v_lshlrev_b32_e32 v124, 16, v103
	v_and_b32_e32 v125, 0xffff0000, v103
	v_lshlrev_b32_e32 v126, 16, v104
	v_and_b32_e32 v127, 0xffff0000, v104
	v_lshlrev_b32_e32 v128, 16, v105
	v_and_b32_e32 v129, 0xffff0000, v105
	v_pk_fma_f32 v[130:131], v[34:35], v[114:115], v[66:67]
	v_pk_fma_f32 v[132:133], v[36:37], v[116:117], v[68:69]
	v_pk_fma_f32 v[134:135], v[38:39], v[118:119], v[70:71]
	v_pk_fma_f32 v[136:137], v[40:41], v[120:121], v[72:73]
	v_pk_fma_f32 v[138:139], v[42:43], v[122:123], v[74:75]
	v_pk_fma_f32 v[140:141], v[44:45], v[124:125], v[76:77]
	v_pk_fma_f32 v[142:143], v[46:47], v[126:127], v[78:79]
	v_pk_fma_f32 v[144:145], v[48:49], v[128:129], v[80:81]
	v_pk_fma_f32 v[66:67], v[18:19], v[114:115], v[82:83]
	v_pk_fma_f32 v[68:69], v[20:21], v[116:117], v[84:85]
	v_pk_fma_f32 v[70:71], v[22:23], v[118:119], v[86:87]
	v_pk_fma_f32 v[72:73], v[24:25], v[120:121], v[88:89]
	v_pk_fma_f32 v[74:75], v[26:27], v[122:123], v[90:91]
	v_pk_fma_f32 v[76:77], v[28:29], v[124:125], v[92:93]
	v_pk_fma_f32 v[78:79], v[30:31], v[126:127], v[94:95]
	v_pk_fma_f32 v[80:81], v[32:33], v[128:129], v[96:97]
	v_pk_fma_f32 v[82:83], v[2:3], v[114:115], v[50:51]
	v_pk_fma_f32 v[84:85], v[4:5], v[116:117], v[52:53]
	v_pk_fma_f32 v[86:87], v[6:7], v[118:119], v[54:55]
	v_pk_fma_f32 v[88:89], v[8:9], v[120:121], v[56:57]
	v_pk_fma_f32 v[90:91], v[10:11], v[122:123], v[58:59]
	v_pk_fma_f32 v[92:93], v[12:13], v[124:125], v[60:61]
	v_pk_fma_f32 v[94:95], v[14:15], v[126:127], v[62:63]
	v_pk_fma_f32 v[96:97], v[16:17], v[128:129], v[64:65]
	v_pk_mul_f32 v[148:149], v[130:131], s[34:35]
	v_pk_mul_f32 v[150:151], v[132:133], s[34:35]
	v_pk_mul_f32 v[152:153], v[134:135], s[34:35]
	v_pk_mul_f32 v[154:155], v[136:137], s[34:35]
	v_exp_f32_e32 v148, v148
	v_exp_f32_e32 v149, v149
	v_exp_f32_e32 v150, v150
	v_exp_f32_e32 v151, v151
	v_exp_f32_e32 v152, v152
	v_exp_f32_e32 v153, v153
	v_exp_f32_e32 v154, v154
	v_exp_f32_e32 v155, v155
	v_pk_add_f32 v[148:149], v[148:149], 1.0 op_sel_hi:[1,0]
	v_pk_add_f32 v[150:151], v[150:151], 1.0 op_sel_hi:[1,0]
	v_pk_add_f32 v[152:153], v[152:153], 1.0 op_sel_hi:[1,0]
	v_pk_add_f32 v[154:155], v[154:155], 1.0 op_sel_hi:[1,0]
	v_rcp_f32_e32 v148, v148
	v_rcp_f32_e32 v149, v149
	v_rcp_f32_e32 v150, v150
	v_rcp_f32_e32 v151, v151
	v_rcp_f32_e32 v152, v152
	v_rcp_f32_e32 v153, v153
	v_rcp_f32_e32 v154, v154
	v_rcp_f32_e32 v155, v155
	v_pk_mul_f32 v[130:131], v[130:131], v[148:149]
	v_pk_mul_f32 v[132:133], v[132:133], v[150:151]
	v_pk_mul_f32 v[134:135], v[134:135], v[152:153]
	v_pk_mul_f32 v[136:137], v[136:137], v[154:155]
	v_pk_mul_f32 v[130:131], v[130:131], v[138:139]
	v_pk_mul_f32 v[132:133], v[132:133], v[140:141]
	v_pk_mul_f32 v[134:135], v[134:135], v[142:143]
	v_pk_mul_f32 v[136:137], v[136:137], v[144:145]
	v_cvt_pk_bf16_f32 v148, v130, v131
	v_cvt_pk_bf16_f32 v149, v132, v133
	v_cvt_pk_bf16_f32 v150, v134, v135
	v_cvt_pk_bf16_f32 v151, v136, v137
	global_store_dwordx4 v159, v[148:151], s[40:41]
	s_add_u32 s40, s40, 0x2c00
	s_addc_u32 s41, s41, 0
	s_waitcnt vmcnt(16)
	ds_read_b128 v[98:101], v160 offset:12288
	ds_read_b128 v[102:105], v160 offset:13312
	s_cmp_gt_u32 s9, 63
	s_cbranch_scc1 .Lcv_dum5
	s_add_i32 m0, s12, 0x2000
	s_add_u32 s26, s42, 0xb000000
	s_addc_u32 s27, s43, 0
	global_load_lds_dwordx4 v159, s[42:43] nt
	s_add_i32 m0, s12, 0x2400
	s_add_u32 s42, s42, 0x2c00
	s_addc_u32 s43, s43, 0
	global_load_lds_dwordx4 v159, s[26:27] nt
	s_branch .Lcv_join5

; __device__ __forceinline__ float sigm(float x) { return 1.f / (1.f + __expf(-x)); }
; __device__ __forceinline__ u32x4 pack8(const float (&f)[8]) { u32x4 w; w.x = pk2(f[0], f[1]); w.y = pk2(f[2], f[3]); w.z = pk2(f[4], f[5]); w.w = pk2(f[6], f[7]); return w; }
; __device__ __forceinline__ void ffn_conv_item(int tid_in, int b, int strip, bf16_t* h1, const bf16_t* h2, const float* cw, const float* cb, bool st = true) {
;     ...
;     for (int blk = 0; blk < 16; ++blk) {
;         u32x4 ng4[4], nv4[4];
;         if (blk + 1 < 16) {
; #pragma unroll
;             for (int j = 0; j < 4; ++j) { const size_t o_ = off0 + (size_t)(32 * (blk + 1) + 8 * j + rl) * 5632; ng4[j] = __builtin_nontemporal_load((const u32x4*)(h1 + o_)); nv4[j] = __builtin_nontemporal_load((const u32x4*)(h2 + o_)); }
;         }
;     ...
;         for (int j = 0; j < 4; ++j) {
;             const size_t off = off0 + (size_t)(32 * blk + 8 * j + rl) * 5632;
;             const u32x4 cgv = cg4[j], cvv = cv4[j];
;             float xg[8], xv[8], yg[8], yv[8]; unpack8(cgv, xg); unpack8(cvv, xv);
; #pragma unroll
;             for (int e = 0; e < 8; ++e) { yg[e] = bg[e] + wg[2][e] * xg[e]; yv[e] = bv[e] + wv[2][e] * xv[e]; }
; #pragma unroll
;             for (int d = 1; d <= 2; ++d) {
;                 const bool own = (rl + d <= 7); const int src = (lane + 64 - 8 * d) & 63;
;                 const u32x4 sg = own ? cgv : pg, sv = own ? cvv : pv;
;                 u32x4 g, v; g.x = __shfl(sg.x, src); g.y = __shfl(sg.y, src); g.z = __shfl(sg.z, src); g.w = __shfl(sg.w, src);
;                 v.x = __shfl(sv.x, src); v.y = __shfl(sv.y, src); v.z = __shfl(sv.z, src); v.w = __shfl(sv.w, src);
;                 float dg[8], dv[8]; unpack8(g, dg); unpack8(v, dv);
; #pragma unroll
;                 for (int e = 0; e < 8; ++e) { yg[e] += wg[2 - d][e] * dg[e]; yv[e] += wv[2 - d][e] * dv[e]; }
;             }
; #pragma unroll
;             for (int e = 0; e < 8; ++e) yg[e] = yg[e] * sigm(yg[e]) * yv[e];
;             { const u32x4 o_ = pack8(yg); if (st) *(u32x4*)(h1 + off) = o_; else asm volatile("" :: "v"(o_)); }
;             pg = cgv; pv = cvv;
;         }
.Lcv_join5:
	s_add_i32 s9, s9, 1
	s_waitcnt lgkmcnt(2)
	v_lshlrev_b32_e32 v114, 16, v106
	v_and_b32_e32 v115, 0xffff0000, v106
	v_lshlrev_b32_e32 v116, 16, v107
	v_and_b32_e32 v117, 0xffff0000, v107
	v_lshlrev_b32_e32 v118, 16, v108
	v_and_b32_e32 v119, 0xffff0000, v108
	v_lshlrev_b32_e32 v120, 16, v109
	v_and_b32_e32 v121, 0xffff0000, v109
	v_lshlrev_b32_e32 v122, 16, v110
	v_and_b32_e32 v123, 0xffff0000, v110
	v_lshlrev_b32_e32 v124, 16, v111
	v_and_b32_e32 v125, 0xffff0000, v111
	v_lshlrev_b32_e32 v126, 16, v112
	v_and_b32_e32 v127, 0xffff0000, v112
	v_lshlrev_b32_e32 v128, 16, v113
	v_and_b32_e32 v129, 0xffff0000, v113
	v_pk_fma_f32 v[130:131], v[34:35], v[114:115], v[66:67]
	v_pk_fma_f32 v[132:133], v[36:37], v[116:117], v[68:69]
	v_pk_fma_f32 v[134:135], v[38:39], v[118:119], v[70:71]
	v_pk_fma_f32 v[136:137], v[40:41], v[120:121], v[72:73]
	v_pk_fma_f32 v[138:139], v[42:43], v[122:123], v[74:75]
	v_pk_fma_f32 v[140:141], v[44:45], v[124:125], v[76:77]
	v_pk_fma_f32 v[142:143], v[46:47], v[126:127], v[78:79]
	v_pk_fma_f32 v[144:145], v[48:49], v[128:129], v[80:81]
	v_pk_fma_f32 v[66:67], v[18:19], v[114:115], v[82:83]
	v_pk_fma_f32 v[68:69], v[20:21], v[116:117], v[84:85]
	v_pk_fma_f32 v[70:71], v[22:23], v[118:119], v[86:87]
	v_pk_fma_f32 v[72:73], v[24:25], v[120:121], v[88:89]
	v_pk_fma_f32 v[74:75], v[26:27], v[122:123], v[90:91]
	v_pk_fma_f32 v[76:77], v[28:29], v[124:125], v[92:93]
	v_pk_fma_f32 v[78:79], v[30:31], v[126:127], v[94:95]
	v_pk_fma_f32 v[80:81], v[32:33], v[128:129], v[96:97]
	v_pk_fma_f32 v[82:83], v[2:3], v[114:115], v[50:51]
	v_pk_fma_f32 v[84:85], v[4:5], v[116:117], v[52:53]
	v_pk_fma_f32 v[86:87], v[6:7], v[118:119], v[54:55]
	v_pk_fma_f32 v[88:89], v[8:9], v[120:121], v[56:57]
	v_pk_fma_f32 v[90:91], v[10:11], v[122:123], v[58:59]
	v_pk_fma_f32 v[92:93], v[12:13], v[124:125], v[60:61]
	v_pk_fma_f32 v[94:95], v[14:15], v[126:127], v[62:63]
	v_pk_fma_f32 v[96:97], v[16:17], v[128:129], v[64:65]
	v_pk_mul_f32 v[148:149], v[130:131], s[34:35]
	v_pk_mul_f32 v[150:151], v[132:133], s[34:35]
	v_pk_mul_f32 v[152:153], v[134:135], s[34:35]
	v_pk_mul_f32 v[154:155], v[136:137], s[34:35]
	v_exp_f32_e32 v148, v148
	v_exp_f32_e32 v149, v149
	v_exp_f32_e32 v150, v150
	v_exp_f32_e32 v151, v151
	v_exp_f32_e32 v152, v152
	v_exp_f32_e32 v153, v153
	v_exp_f32_e32 v154, v154
	v_exp_f32_e32 v155, v155
	v_pk_add_f32 v[148:149], v[148:149], 1.0 op_sel_hi:[1,0]
	v_pk_add_f32 v[150:151], v[150:151], 1.0 op_sel_hi:[1,0]
	v_pk_add_f32 v[152:153], v[152:153], 1.0 op_sel_hi:[1,0]
	v_pk_add_f32 v[154:155], v[154:155], 1.0 op_sel_hi:[1,0]
	v_rcp_f32_e32 v148, v148
	v_rcp_f32_e32 v149, v149
	v_rcp_f32_e32 v150, v150
	v_rcp_f32_e32 v151, v151
	v_rcp_f32_e32 v152, v152
	v_rcp_f32_e32 v153, v153
	v_rcp_f32_e32 v154, v154
	v_rcp_f32_e32 v155, v155
	v_pk_mul_f32 v[130:131], v[130:131], v[148:149]
	v_pk_mul_f32 v[132:133], v[132:133], v[150:151]
	v_pk_mul_f32 v[134:135], v[134:135], v[152:153]
	v_pk_mul_f32 v[136:137], v[136:137], v[154:155]
	v_pk_mul_f32 v[130:131], v[130:131], v[138:139]
	v_pk_mul_f32 v[132:133], v[132:133], v[140:141]
	v_pk_mul_f32 v[134:135], v[134:135], v[142:143]
	v_pk_mul_f32 v[136:137], v[136:137], v[144:145]
	v_cvt_pk_bf16_f32 v148, v130, v131
	v_cvt_pk_bf16_f32 v149, v132, v133
	v_cvt_pk_bf16_f32 v150, v134, v135
	v_cvt_pk_bf16_f32 v151, v136, v137
	global_store_dwordx4 v159, v[148:151], s[40:41]
	s_add_u32 s40, s40, 0x2c00
	s_addc_u32 s41, s41, 0
	s_waitcnt vmcnt(16)
	ds_read_b128 v[106:109], v160 offset:14336
	ds_read_b128 v[110:113], v160 offset:15360
	s_cmp_gt_u32 s9, 63
	s_cbranch_scc1 .Lcv_dum6
	s_add_i32 m0, s12, 0x2800
	s_add_u32 s26, s42, 0xb000000
	s_addc_u32 s27, s43, 0
	global_load_lds_dwordx4 v159, s[42:43] nt
	s_add_i32 m0, s12, 0x2c00
	s_add_u32 s42, s42, 0x2c00
	s_addc_u32 s43, s43, 0
	global_load_lds_dwordx4 v159, s[26:27] nt
	s_branch .Lcv_join6

; __device__ __forceinline__ float sigm(float x) { return 1.f / (1.f + __expf(-x)); }
; __device__ __forceinline__ u32x4 pack8(const float (&f)[8]) { u32x4 w; w.x = pk2(f[0], f[1]); w.y = pk2(f[2], f[3]); w.z = pk2(f[4], f[5]); w.w = pk2(f[6], f[7]); return w; }
; __device__ __forceinline__ void ffn_conv_item(int tid_in, int b, int strip, bf16_t* h1, const bf16_t* h2, const float* cw, const float* cb, bool st = true) {
;     ...
;         for (int j = 0; j < 4; ++j) {
;             const size_t off = off0 + (size_t)(32 * blk + 8 * j + rl) * 5632;
;             const u32x4 cgv = cg4[j], cvv = cv4[j];
;             float xg[8], xv[8], yg[8], yv[8]; unpack8(cgv, xg); unpack8(cvv, xv);
; #pragma unroll
;             for (int e = 0; e < 8; ++e) { yg[e] = bg[e] + wg[2][e] * xg[e]; yv[e] = bv[e] + wv[2][e] * xv[e]; }
; #pragma unroll
;             for (int d = 1; d <= 2; ++d) {
;                 const bool own = (rl + d <= 7); const int src = (lane + 64 - 8 * d) & 63;
;                 const u32x4 sg = own ? cgv : pg, sv = own ? cvv : pv;
;                 u32x4 g, v; g.x = __shfl(sg.x, src); g.y = __shfl(sg.y, src); g.z = __shfl(sg.z, src); g.w = __shfl(sg.w, src);
;                 v.x = __shfl(sv.x, src); v.y = __shfl(sv.y, src); v.z = __shfl(sv.z, src); v.w = __shfl(sv.w, src);
;                 float dg[8], dv[8]; unpack8(g, dg); unpack8(v, dv);
; #pragma unroll
;                 for (int e = 0; e < 8; ++e) { yg[e] += wg[2 - d][e] * dg[e]; yv[e] += wv[2 - d][e] * dv[e]; }
;             }
; #pragma unroll
;             for (int e = 0; e < 8; ++e) yg[e] = yg[e] * sigm(yg[e]) * yv[e];
;             { const u32x4 o_ = pack8(yg); if (st) *(u32x4*)(h1 + off) = o_; else asm volatile("" :: "v"(o_)); }
;             pg = cgv; pv = cvv;
;         }
.Lcv_join6:
	s_add_i32 s9, s9, 1
	s_waitcnt lgkmcnt(2)
	v_lshlrev_b32_e32 v114, 16, v98
	v_and_b32_e32 v115, 0xffff0000, v98
	v_lshlrev_b32_e32 v116, 16, v99
	v_and_b32_e32 v117, 0xffff0000, v99
	v_lshlrev_b32_e32 v118, 16, v100
	v_and_b32_e32 v119, 0xffff0000, v100
	v_lshlrev_b32_e32 v120, 16, v101
	v_and_b32_e32 v121, 0xffff0000, v101
	v_lshlrev_b32_e32 v122, 16, v102
	v_and_b32_e32 v123, 0xffff0000, v102
	v_lshlrev_b32_e32 v124, 16, v103
	v_and_b32_e32 v125, 0xffff0000, v103
	v_lshlrev_b32_e32 v126, 16, v104
	v_and_b32_e32 v127, 0xffff0000, v104
	v_lshlrev_b32_e32 v128, 16, v105
	v_and_b32_e32 v129, 0xffff0000, v105
	v_pk_fma_f32 v[130:131], v[34:35], v[114:115], v[66:67]
	v_pk_fma_f32 v[132:133], v[36:37], v[116:117], v[68:69]
	v_pk_fma_f32 v[134:135], v[38:39], v[118:119], v[70:71]
	v_pk_fma_f32 v[136:137], v[40:41], v[120:121], v[72:73]
	v_pk_fma_f32 v[138:139], v[42:43], v[122:123], v[74:75]
	v_pk_fma_f32 v[140:141], v[44:45], v[124:125], v[76:77]
	v_pk_fma_f32 v[142:143], v[46:47], v[126:127], v[78:79]
	v_pk_fma_f32 v[144:145], v[48:49], v[128:129], v[80:81]
	v_pk_fma_f32 v[66:67], v[18:19], v[114:115], v[82:83]
	v_pk_fma_f32 v[68:69], v[20:21], v[116:117], v[84:85]
	v_pk_fma_f32 v[70:71], v[22:23], v[118:119], v[86:87]
	v_pk_fma_f32 v[72:73], v[24:25], v[120:121], v[88:89]
	v_pk_fma_f32 v[74:75], v[26:27], v[122:123], v[90:91]
	v_pk_fma_f32 v[76:77], v[28:29], v[124:125], v[92:93]
	v_pk_fma_f32 v[78:79], v[30:31], v[126:127], v[94:95]
	v_pk_fma_f32 v[80:81], v[32:33], v[128:129], v[96:97]
	v_pk_fma_f32 v[82:83], v[2:3], v[114:115], v[50:51]
	v_pk_fma_f32 v[84:85], v[4:5], v[116:117], v[52:53]
	v_pk_fma_f32 v[86:87], v[6:7], v[118:119], v[54:55]
	v_pk_fma_f32 v[88:89], v[8:9], v[120:121], v[56:57]
	v_pk_fma_f32 v[90:91], v[10:11], v[122:123], v[58:59]
	v_pk_fma_f32 v[92:93], v[12:13], v[124:125], v[60:61]
	v_pk_fma_f32 v[94:95], v[14:15], v[126:127], v[62:63]
	v_pk_fma_f32 v[96:97], v[16:17], v[128:129], v[64:65]
	v_pk_mul_f32 v[148:149], v[130:131], s[34:35]
	v_pk_mul_f32 v[150:151], v[132:133], s[34:35]
	v_pk_mul_f32 v[152:153], v[134:135], s[34:35]
	v_pk_mul_f32 v[154:155], v[136:137], s[34:35]
	v_exp_f32_e32 v148, v148
	v_exp_f32_e32 v149, v149
	v_exp_f32_e32 v150, v150
	v_exp_f32_e32 v151, v151
	v_exp_f32_e32 v152, v152
	v_exp_f32_e32 v153, v153
	v_exp_f32_e32 v154, v154
	v_exp_f32_e32 v155, v155
	v_pk_add_f32 v[148:149], v[148:149], 1.0 op_sel_hi:[1,0]
	v_pk_add_f32 v[150:151], v[150:151], 1.0 op_sel_hi:[1,0]
	v_pk_add_f32 v[152:153], v[152:153], 1.0 op_sel_hi:[1,0]
	v_pk_add_f32 v[154:155], v[154:155], 1.0 op_sel_hi:[1,0]
	v_rcp_f32_e32 v148, v148
	v_rcp_f32_e32 v149, v149
	v_rcp_f32_e32 v150, v150
	v_rcp_f32_e32 v151, v151
	v_rcp_f32_e32 v152, v152
	v_rcp_f32_e32 v153, v153
	v_rcp_f32_e32 v154, v154
	v_rcp_f32_e32 v155, v155
	v_pk_mul_f32 v[130:131], v[130:131], v[148:149]
	v_pk_mul_f32 v[132:133], v[132:133], v[150:151]
	v_pk_mul_f32 v[134:135], v[134:135], v[152:153]
	v_pk_mul_f32 v[136:137], v[136:137], v[154:155]
	v_pk_mul_f32 v[130:131], v[130:131], v[138:139]
	v_pk_mul_f32 v[132:133], v[132:133], v[140:141]
	v_pk_mul_f32 v[134:135], v[134:135], v[142:143]
	v_pk_mul_f32 v[136:137], v[136:137], v[144:145]
	v_cvt_pk_bf16_f32 v148, v130, v131
	v_cvt_pk_bf16_f32 v149, v132, v133
	v_cvt_pk_bf16_f32 v150, v134, v135
	v_cvt_pk_bf16_f32 v151, v136, v137
	global_store_dwordx4 v159, v[148:151], s[40:41]
	s_add_u32 s40, s40, 0x2c00
	s_addc_u32 s41, s41, 0
	s_waitcnt vmcnt(16)
	ds_read_b128 v[98:101], v160 offset:0
	ds_read_b128 v[102:105], v160 offset:1024
	s_cmp_gt_u32 s9, 63
	s_cbranch_scc1 .Lcv_dum7
	s_add_i32 m0, s12, 0x3000
	s_add_u32 s26, s42, 0xb000000
	s_addc_u32 s27, s43, 0
	global_load_lds_dwordx4 v159, s[42:43] nt
	s_add_i32 m0, s12, 0x3400
	s_add_u32 s42, s42, 0x2c00
	s_addc_u32 s43, s43, 0
	global_load_lds_dwordx4 v159, s[26:27] nt
	s_branch .Lcv_join7

; __device__ __forceinline__ float sigm(float x) { return 1.f / (1.f + __expf(-x)); }
; __device__ __forceinline__ u32x4 pack8(const float (&f)[8]) { u32x4 w; w.x = pk2(f[0], f[1]); w.y = pk2(f[2], f[3]); w.z = pk2(f[4], f[5]); w.w = pk2(f[6], f[7]); return w; }
; __device__ __forceinline__ void ffn_conv_item(int tid_in, int b, int strip, bf16_t* h1, const bf16_t* h2, const float* cw, const float* cb, bool st = true) {
;     ...
;         for (int j = 0; j < 4; ++j) {
;             const size_t off = off0 + (size_t)(32 * blk + 8 * j + rl) * 5632;
;             const u32x4 cgv = cg4[j], cvv = cv4[j];
;             float xg[8], xv[8], yg[8], yv[8]; unpack8(cgv, xg); unpack8(cvv, xv);
; #pragma unroll
;             for (int e = 0; e < 8; ++e) { yg[e] = bg[e] + wg[2][e] * xg[e]; yv[e] = bv[e] + wv[2][e] * xv[e]; }
; #pragma unroll
;             for (int d = 1; d <= 2; ++d) {
;                 const bool own = (rl + d <= 7); const int src = (lane + 64 - 8 * d) & 63;
;                 const u32x4 sg = own ? cgv : pg, sv = own ? cvv : pv;
;                 u32x4 g, v; g.x = __shfl(sg.x, src); g.y = __shfl(sg.y, src); g.z = __shfl(sg.z, src); g.w = __shfl(sg.w, src);
;                 v.x = __shfl(sv.x, src); v.y = __shfl(sv.y, src); v.z = __shfl(sv.z, src); v.w = __shfl(sv.w, src);
;                 float dg[8], dv[8]; unpack8(g, dg); unpack8(v, dv);
; #pragma unroll
;                 for (int e = 0; e < 8; ++e) { yg[e] += wg[2 - d][e] * dg[e]; yv[e] += wv[2 - d][e] * dv[e]; }
;             }
; #pragma unroll
;             for (int e = 0; e < 8; ++e) yg[e] = yg[e] * sigm(yg[e]) * yv[e];
;             { const u32x4 o_ = pack8(yg); if (st) *(u32x4*)(h1 + off) = o_; else asm volatile("" :: "v"(o_)); }
;             pg = cgv; pv = cvv;
;         }
; #pragma unroll
;         for (int j = 0; j < 4; ++j) { cg4[j] = ng4[j]; cv4[j] = nv4[j]; }
;     }
.Lcv_join7:
	s_add_i32 s9, s9, 1
	s_waitcnt lgkmcnt(2)
	v_lshlrev_b32_e32 v114, 16, v106
	v_and_b32_e32 v115, 0xffff0000, v106
	v_lshlrev_b32_e32 v116, 16, v107
	v_and_b32_e32 v117, 0xffff0000, v107
	v_lshlrev_b32_e32 v118, 16, v108
	v_and_b32_e32 v119, 0xffff0000, v108
	v_lshlrev_b32_e32 v120, 16, v109
	v_and_b32_e32 v121, 0xffff0000, v109
	v_lshlrev_b32_e32 v122, 16, v110
	v_and_b32_e32 v123, 0xffff0000, v110
	v_lshlrev_b32_e32 v124, 16, v111
	v_and_b32_e32 v125, 0xffff0000, v111
	v_lshlrev_b32_e32 v126, 16, v112
	v_and_b32_e32 v127, 0xffff0000, v112
	v_lshlrev_b32_e32 v128, 16, v113
	v_and_b32_e32 v129, 0xffff0000, v113
	v_pk_fma_f32 v[130:131], v[34:35], v[114:115], v[66:67]
	v_pk_fma_f32 v[132:133], v[36:37], v[116:117], v[68:69]
	v_pk_fma_f32 v[134:135], v[38:39], v[118:119], v[70:71]
	v_pk_fma_f32 v[136:137], v[40:41], v[120:121], v[72:73]
	v_pk_fma_f32 v[138:139], v[42:43], v[122:123], v[74:75]
	v_pk_fma_f32 v[140:141], v[44:45], v[124:125], v[76:77]
	v_pk_fma_f32 v[142:143], v[46:47], v[126:127], v[78:79]
	v_pk_fma_f32 v[144:145], v[48:49], v[128:129], v[80:81]
	v_pk_fma_f32 v[66:67], v[18:19], v[114:115], v[82:83]
	v_pk_fma_f32 v[68:69], v[20:21], v[116:117], v[84:85]
	v_pk_fma_f32 v[70:71], v[22:23], v[118:119], v[86:87]
	v_pk_fma_f32 v[72:73], v[24:25], v[120:121], v[88:89]
	v_pk_fma_f32 v[74:75], v[26:27], v[122:123], v[90:91]
	v_pk_fma_f32 v[76:77], v[28:29], v[124:125], v[92:93]
	v_pk_fma_f32 v[78:79], v[30:31], v[126:127], v[94:95]
	v_pk_fma_f32 v[80:81], v[32:33], v[128:129], v[96:97]
	v_pk_fma_f32 v[82:83], v[2:3], v[114:115], v[50:51]
	v_pk_fma_f32 v[84:85], v[4:5], v[116:117], v[52:53]
	v_pk_fma_f32 v[86:87], v[6:7], v[118:119], v[54:55]
	v_pk_fma_f32 v[88:89], v[8:9], v[120:121], v[56:57]
	v_pk_fma_f32 v[90:91], v[10:11], v[122:123], v[58:59]
	v_pk_fma_f32 v[92:93], v[12:13], v[124:125], v[60:61]
	v_pk_fma_f32 v[94:95], v[14:15], v[126:127], v[62:63]
	v_pk_fma_f32 v[96:97], v[16:17], v[128:129], v[64:65]
	v_pk_mul_f32 v[148:149], v[130:131], s[34:35]
	v_pk_mul_f32 v[150:151], v[132:133], s[34:35]
	v_pk_mul_f32 v[152:153], v[134:135], s[34:35]
	v_pk_mul_f32 v[154:155], v[136:137], s[34:35]
	v_exp_f32_e32 v148, v148
	v_exp_f32_e32 v149, v149
	v_exp_f32_e32 v150, v150
	v_exp_f32_e32 v151, v151
	v_exp_f32_e32 v152, v152
	v_exp_f32_e32 v153, v153
	v_exp_f32_e32 v154, v154
	v_exp_f32_e32 v155, v155
	v_pk_add_f32 v[148:149], v[148:149], 1.0 op_sel_hi:[1,0]
	v_pk_add_f32 v[150:151], v[150:151], 1.0 op_sel_hi:[1,0]
	v_pk_add_f32 v[152:153], v[152:153], 1.0 op_sel_hi:[1,0]
	v_pk_add_f32 v[154:155], v[154:155], 1.0 op_sel_hi:[1,0]
	v_rcp_f32_e32 v148, v148
	v_rcp_f32_e32 v149, v149
	v_rcp_f32_e32 v150, v150
	v_rcp_f32_e32 v151, v151
	v_rcp_f32_e32 v152, v152
	v_rcp_f32_e32 v153, v153
	v_rcp_f32_e32 v154, v154
	v_rcp_f32_e32 v155, v155
	v_pk_mul_f32 v[130:131], v[130:131], v[148:149]
	v_pk_mul_f32 v[132:133], v[132:133], v[150:151]
	v_pk_mul_f32 v[134:135], v[134:135], v[152:153]
	v_pk_mul_f32 v[136:137], v[136:137], v[154:155]
	v_pk_mul_f32 v[130:131], v[130:131], v[138:139]
	v_pk_mul_f32 v[132:133], v[132:133], v[140:141]
	v_pk_mul_f32 v[134:135], v[134:135], v[142:143]
	v_pk_mul_f32 v[136:137], v[136:137], v[144:145]
	v_cvt_pk_bf16_f32 v148, v130, v131
	v_cvt_pk_bf16_f32 v149, v132, v133
	v_cvt_pk_bf16_f32 v150, v134, v135
	v_cvt_pk_bf16_f32 v151, v136, v137
	global_store_dwordx4 v159, v[148:151], s[40:41]
	s_add_u32 s40, s40, 0x2c00
	s_addc_u32 s41, s41, 0
	s_add_i32 s13, s13, 1
	s_cmp_lt_u32 s13, 8
	s_cbranch_scc1 .Lcv_loop
	s_branch .LBB0_17
	s_nop 0
	s_nop 0
	s_nop 0
	s_nop 0
	s_nop 0
	s_nop 0
	s_nop 0
	s_nop 0
	s_nop 0
	s_nop 0
	s_nop 0
	s_nop 0
	s_nop 0
	s_nop 0
	s_nop 0
	s_nop 0
	s_nop 0
	s_nop 0
	s_nop 0
	s_nop 0
	s_nop 0
	s_nop 0
	s_nop 0
	s_nop 0
	s_nop 0
	s_nop 0
	s_nop 0
	s_nop 0
	s_nop 0
	s_nop 0
	s_nop 0
	s_nop 0
	s_nop 0
	s_nop 0
	s_nop 0
	s_nop 0
	s_nop 0
	s_nop 0
	s_nop 0
	s_nop 0
	s_nop 0
	s_nop 0
	s_nop 0
	s_nop 0
	s_nop 0
	s_nop 0
	s_nop 0
	s_nop 0
	s_nop 0
	s_nop 0
	s_nop 0
	s_nop 0
	s_nop 0
	s_nop 0
	s_nop 0
	s_nop 0
	s_nop 0
	s_nop 0
	s_nop 0
	s_nop 0
	s_nop 0
	s_nop 0
	s_nop 0
	s_nop 0
	s_nop 0
	s_nop 0
	s_nop 0
	s_nop 0
	s_nop 0
	s_nop 0
	s_nop 0
	s_nop 0
	s_nop 0
	s_nop 0
	s_nop 0
	s_nop 0
	s_nop 0
	s_nop 0
	s_nop 0
	s_nop 0
	s_nop 0
	s_nop 0
	s_nop 0
	s_nop 0
	s_nop 0
	s_nop 0
	s_nop 0
	s_nop 0
	s_nop 0
	s_nop 0
	s_nop 0
	s_nop 0
	s_nop 0
	s_nop 0
	s_nop 0
	s_nop 0
	s_nop 0
	s_nop 0
	s_nop 0
	s_nop 0
	s_nop 0
	s_nop 0
	s_nop 0
	s_nop 0
	s_nop 0
	s_nop 0
	s_nop 0
	s_nop 0
	s_nop 0
	s_nop 0
	s_nop 0
	s_nop 0
	s_nop 0
	s_nop 0
	s_nop 0
	s_nop 0
	s_nop 0
	s_nop 0
	s_nop 0
	s_nop 0
	s_nop 0
	s_nop 0
	s_nop 0
	s_nop 0
	s_nop 0
	s_nop 0
	s_nop 0
	s_nop 0
	s_nop 0
	s_nop 0
	s_nop 0
	s_nop 0
	s_nop 0
	s_nop 0
	s_nop 0
	s_nop 0
	s_nop 0
	s_nop 0
	s_nop 0
	s_nop 0
	s_nop 0
	s_nop 0
	s_nop 0
	s_nop 0
	s_nop 0
	s_nop 0
	s_nop 0
	s_nop 0
	s_nop 0
	s_nop 0
	s_nop 0
	s_nop 0
	s_nop 0
	s_nop 0
	s_nop 0
	s_nop 0
	s_nop 0
	s_nop 0
	s_nop 0
	s_nop 0
	s_nop 0
	s_nop 0
	s_nop 0
	s_nop 0
	s_nop 0
	s_nop 0
	s_nop 0
	s_nop 0
	s_nop 0
	s_nop 0
	s_nop 0
	s_nop 0
	s_nop 0
	s_nop 0
	s_nop 0
	s_nop 0
	s_nop 0
	s_nop 0
	s_nop 0
	s_nop 0
	s_nop 0
	s_nop 0
	s_nop 0
	s_nop 0
	s_nop 0
	s_nop 0
	s_nop 0
	s_nop 0
	s_nop 0
	s_nop 0
	s_nop 0
	s_nop 0
	s_nop 0
	s_nop 0
	s_nop 0
	s_nop 0
	s_nop 0
	s_nop 0
	s_nop 0
	s_nop 0
	s_nop 0
	s_nop 0
	s_nop 0
	s_nop 0
	s_nop 0
	s_nop 0
	s_nop 0
	s_nop 0
	s_nop 0
	s_nop 0
	s_nop 0
	s_nop 0
	s_nop 0
	s_nop 0
	s_nop 0
	s_nop 0
	s_nop 0
	s_nop 0
	s_nop 0
	s_nop 0
	s_nop 0
	s_nop 0
	s_nop 0
	s_nop 0
	s_nop 0
	s_nop 0
	s_nop 0
	s_nop 0
	s_nop 0
	s_nop 0
	s_nop 0
	s_nop 0
	s_nop 0
	s_nop 0
	s_nop 0
	s_nop 0
	s_nop 0
	s_nop 0
	s_nop 0
	s_nop 0
	s_nop 0
	s_nop 0
	s_nop 0
	s_nop 0
	s_nop 0
	s_nop 0
	s_nop 0
	s_nop 0
	s_nop 0
	s_nop 0
	s_nop 0
	s_nop 0
	s_nop 0
	s_nop 0
	s_nop 0
	s_nop 0
	s_nop 0
	s_nop 0
	s_nop 0
	s_nop 0
	s_nop 0
	s_nop 0
	s_nop 0
	s_nop 0
	s_nop 0
	s_nop 0
	s_nop 0
	s_nop 0
	s_nop 0
	s_nop 0
	s_nop 0
	s_nop 0
	s_nop 0
	s_nop 0
	s_nop 0
	s_nop 0
	s_nop 0
	s_nop 0
	s_nop 0
	s_nop 0
	s_nop 0
	s_nop 0
	s_nop 0
	s_nop 0
	s_nop 0
	s_nop 0
	s_nop 0
	s_nop 0
	s_nop 0
	s_nop 0
	s_nop 0
	s_nop 0
	s_nop 0
	s_nop 0
	s_nop 0
	s_nop 0
	s_nop 0
	s_nop 0
	s_nop 0
	s_nop 0
	s_nop 0
	s_nop 0
	s_nop 0
	s_nop 0
	s_nop 0
	s_nop 0
	s_nop 0
	s_nop 0
	s_nop 0
	s_nop 0
	s_nop 0
	s_nop 0
	s_nop 0
	s_nop 0
	s_nop 0
	s_nop 0
	s_nop 0
	s_nop 0
	s_nop 0
	s_nop 0
	s_nop 0
	s_nop 0
	s_nop 0
	s_nop 0
	s_nop 0
	s_nop 0
	s_nop 0
	s_nop 0
	s_nop 0
	s_nop 0
	s_nop 0
	s_nop 0
	s_nop 0
	s_nop 0
	s_nop 0
	s_nop 0
	s_nop 0
	s_nop 0
	s_nop 0
	s_nop 0
	s_nop 0
	s_nop 0
	s_nop 0
	s_nop 0
	s_nop 0
	s_nop 0
	s_nop 0
	s_nop 0
	s_nop 0
	s_nop 0
	s_nop 0
	s_nop 0
	s_nop 0
	s_nop 0
	s_nop 0
	s_nop 0
	s_nop 0
	s_nop 0
	s_nop 0
	s_nop 0
	s_nop 0
	s_nop 0
	s_nop 0
	s_nop 0
	s_nop 0
